# scan: both halves of a workgroup share the Q/K/KT staging and the masked P block (half the global loads and LDS writes)
# speedup vs baseline: 1.1333x; 1.0389x over previous
; DEV int tidx() { return tidx_full() & 255; }
; DEV void scan_item_mfma(const Params& p, int g, int item, char* smem) {
;   const int L = g ? 8192 : 4096;
;   const int NC = L / 64;
;   const int vs = item & 3, dir = (item >> 2) & 1, h = (item >> 3) & 3, b = item >> 5;
;   char* Qs = smem;
;   char* Ks = Qs + 17408;
;   char* KTs = Ks + 17408;
;   char* Vts = KTs + 18432;
;   char* Ps = Vts + 4608;
;   char* Sts = Ps + 9216;
;   float* decs = (float*)(Sts + 8704);
;   u16* PHG = (u16*)(p.ws + OFF_PHG);
;   const u16* QK = (const u16*)(p.out + (size_t)g * NTOK * D);
;   const u16* Qp = QK + (size_t)(2 * dir) * NTOK * 512;
;   const u16* Kp = Qp + (size_t)NTOK * 512;
;   const u16* KT = (const u16*)(p.ws + OFF_KT);
;   const float* DEC = (const float*)(p.ws + OFF_DEC);
;   const int tid = tidx();
;   const int wave = __builtin_amdgcn_readfirstlane(tid >> 6);
;   const int lane = tid & 63, r = lane & 31, hh = lane >> 5;
;   __syncthreads();
;   for (int e = tid; e < 8704 / 16; e += 256) ((uint4*)Sts)[e] = make_uint4(0, 0, 0, 0);
;   f32x16 accS[2];
; #pragma unroll
;   for (int t = 0; t < 2; ++t)
; #pragma unroll
;     for (int i = 0; i < 16; ++i) accS[t][i] = 0.f;
;   const int ocol = (dir ? 1024 : 0) + h * 128 + vs * 32;
;   uint4 q0, q1, q2, q3, k0, k1, k2, k3, t0, t1, t2, t3, vv;
;   float dd = 0.f;
;   const int qrow = tid >> 4, qc = tid & 15;
;   const int trow = tid >> 3, tc = tid & 7;
;   const int vrow = tid >> 2, vc = tid & 3;
.LBB0_667:
	s_movk_i32 s40, 0x1400
	s_or_b64 exec, exec, s[0:1]
	s_and_b64 s[0:1], s[66:67], exec
	v_readfirstlane_b32 s24, v202
	s_cselect_b32 s0, 0x100, s61
	s_lshr_b32 s26, s24, 8
	s_cmp_ge_i32 s81, s0
	s_waitcnt lgkmcnt(0)
	s_barrier
	s_cbranch_scc1 .LBB0_720
	v_writelane_b32 v160, s0, 0
	v_writelane_b32 v160, s1, 1
	v_writelane_b32 v160, s2, 2
	v_writelane_b32 v160, s3, 3
	v_writelane_b32 v160, s4, 4
	v_writelane_b32 v160, s5, 5
	v_writelane_b32 v160, s6, 6
	v_writelane_b32 v160, s7, 7
	v_writelane_b32 v160, s8, 8
	v_writelane_b32 v160, s9, 9
	v_writelane_b32 v160, s10, 10
	v_writelane_b32 v160, s11, 11
	v_writelane_b32 v160, s12, 12
	v_writelane_b32 v160, s13, 13
	v_writelane_b32 v160, s14, 14
	v_writelane_b32 v160, s15, 15
	v_writelane_b32 v160, s16, 16
	v_writelane_b32 v160, s17, 17
	v_writelane_b32 v160, s18, 18
	v_writelane_b32 v160, s19, 19
	v_writelane_b32 v160, s20, 20
	v_writelane_b32 v160, s21, 21
	v_writelane_b32 v160, s22, 22
	v_writelane_b32 v160, s23, 23
	v_writelane_b32 v160, s24, 24
	v_writelane_b32 v160, s25, 25
	v_writelane_b32 v160, s26, 26
	v_writelane_b32 v160, s27, 27
	v_writelane_b32 v160, s28, 28
	v_writelane_b32 v160, s29, 29
	v_writelane_b32 v160, s30, 30
	v_writelane_b32 v160, s31, 31
	v_writelane_b32 v160, s33, 33
	v_writelane_b32 v160, s34, 34
	v_writelane_b32 v160, s35, 35
	v_writelane_b32 v160, s36, 36
	v_writelane_b32 v160, s37, 37
	v_writelane_b32 v160, s38, 38
	v_writelane_b32 v160, s39, 39
	v_writelane_b32 v160, s40, 40
	v_writelane_b32 v160, s41, 41
	v_writelane_b32 v160, s42, 42
	v_writelane_b32 v160, s43, 43
	v_writelane_b32 v160, s44, 44
	v_writelane_b32 v160, s45, 45
	v_writelane_b32 v160, s46, 46
	v_writelane_b32 v160, s47, 47
	v_writelane_b32 v160, s48, 48
	v_writelane_b32 v160, s49, 49
	v_writelane_b32 v160, s50, 50
	v_writelane_b32 v160, s51, 51
	v_writelane_b32 v160, s52, 52
	v_writelane_b32 v160, s53, 53
	v_writelane_b32 v160, s54, 54
	v_writelane_b32 v160, s55, 55
	v_writelane_b32 v160, s56, 56
	v_writelane_b32 v160, s57, 57
	v_writelane_b32 v160, s58, 58
	v_writelane_b32 v160, s59, 59
	v_writelane_b32 v160, s60, 60
	v_writelane_b32 v160, s61, 61
	v_writelane_b32 v160, s62, 62
	v_writelane_b32 v160, s63, 63
	v_writelane_b32 v161, s64, 0
	v_writelane_b32 v161, s65, 1
	v_writelane_b32 v161, s66, 2
	v_writelane_b32 v161, s67, 3
	v_writelane_b32 v161, s68, 4
	v_writelane_b32 v161, s69, 5
	v_writelane_b32 v161, s70, 6
	v_writelane_b32 v161, s71, 7
	v_writelane_b32 v161, s72, 8
	v_writelane_b32 v161, s73, 9
	s_barrier
	s_add_i32 s2, s26, s81
	s_and_b32 s3, s2, 3
	s_bfe_u32 s4, s2, 0x10002
	s_bfe_u32 s5, s2, 0x20003
	s_lshr_b32 s6, s2, 5
	s_and_b64 s[0:1], s[66:67], exec
	s_cselect_b32 s7, 64, 0x80
	s_bfe_u32 s9, s24, 0x20006
	s_mul_i32 s31, s26, 0x3600
	s_add_u32 s31, s31, 0xf400
	v_and_b32_e32 v53, 0xff, v202
	v_and_b32_e32 v54, 63, v202
	v_and_b32_e32 v55, 31, v202
	v_bfe_u32 v109, v202, 5, 1
	v_bfe_u32 v110, v202, 6, 2
	v_and_b32_e32 v111, 0x1ff, v202
	v_lshrrev_b32_e32 v220, 4, v111
	v_and_b32_e32 v221, 15, v111
	v_lshlrev_b32_e32 v219, 4, v221
	v_lshl_add_u32 v209, v220, 10, v219
	v_add_u32_e32 v210, 0x8000, v209
	v_mul_u32_u24_e32 v248, 0x110, v220
	v_add_u32_e32 v234, v248, v219
	v_lshrrev_b32_e32 v220, 3, v111
	v_and_b32_e32 v221, 7, v111
	v_lshlrev_b32_e32 v219, 4, v221
	v_lshl_add_u32 v213, v220, 7, v219
	v_add_u32_e32 v214, 0x2000, v213
	v_mul_u32_u24_e32 v248, 0x90, v220
	v_add_u32_e32 v235, v248, v219
	v_lshrrev_b32_e32 v220, 2, v53
	v_and_b32_e32 v221, 3, v53
	v_mul_u32_u24_e32 v219, 0x1400, v220
	v_lshl_add_u32 v215, v221, 4, v219
	v_mul_u32_u24_e32 v219, 0x480, v221
	v_lshl_add_u32 v219, v220, 1, v219
	v_add_u32_e32 v236, s31, v219
	v_and_b32_e32 v220, 0x7f, v53
	v_lshlrev_b32_e32 v216, 2, v220
	v_add_u32_e32 v237, s31, v216
	v_mul_u32_u24_e32 v220, 0x110, v55
	v_mul_u32_u24_e32 v221, 0x90, v55
	v_lshlrev_b32_e32 v219, 4, v109
	v_add_u32_e32 v164, v220, v219
	v_add3_u32 v245, v220, v219, s31
	v_add3_u32 v244, v221, v219, s31
	v_add_u32_e32 v111, v221, v219
	v_lshrrev_b32_e32 v248, 1, v110
	v_mul_u32_u24_e32 v248, 0x2200, v248
	v_add_u32_e32 v240, v164, v248
	v_and_b32_e32 v248, 1, v110
	v_mul_u32_u24_e32 v248, 0x2200, v248
	v_add_u32_e32 v242, v164, v248
	v_mul_u32_u24_e32 v248, 0x2200, v110
	v_add_u32_e32 v241, v164, v248
	v_mul_u32_u24_e32 v248, 0x1200, v110
	v_add_u32_e32 v243, v111, v248
	v_lshrrev_b32_e32 v248, 1, v110
	v_mul_u32_u24_e32 v248, 0x1200, v248
	v_add_u32_e32 v239, v221, v248
	v_and_b32_e32 v248, 1, v110
	v_lshlrev_b32_e32 v248, 6, v248
	v_lshl_add_u32 v248, v109, 3, v248
	v_add_u32_e32 v239, v239, v248
	v_subrev_u32_e32 v248, 2, v110
	v_lshlrev_b32_e32 v219, 7, v248
	v_lshl_add_u32 v219, v109, 3, v219
	v_add3_u32 v238, v220, v219, s31
	v_mul_u32_u24_e32 v219, 0x2400, v248
	v_add_u32_e32 v207, v111, v219
	v_lshlrev_b32_e32 v219, 8, v248
	v_lshl_add_u32 v219, v109, 4, v219
	v_add_u32_e32 v208, s31, v219
	v_lshl_add_u32 v219, v110, 5, v55
	v_mul_u32_u24_e32 v219, 0x1400, v219
	v_lshl_add_u32 v217, v109, 3, v219
	v_lshlrev_b32_e32 v219, 2, v109
	v_sub_u32_e32 v218, v55, v219
	s_cmp_eq_u32 s4, 0
	s_cbranch_scc0 .Lscan_d1
; DEV void scan_item_mfma(const Params& p, int g, int item, char* smem) {
;     ...
;   __syncthreads();
;   for (int e = tid; e < 8704 / 16; e += 256) ((uint4*)Sts)[e] = make_uint4(0, 0, 0, 0);
;   f32x16 accS[2];
; #pragma unroll
;   for (int t = 0; t < 2; ++t)
; #pragma unroll
;     for (int i = 0; i < 16; ++i) accS[t][i] = 0.f;
;   const int ocol = (dir ? 1024 : 0) + h * 128 + vs * 32;
;   uint4 q0, q1, q2, q3, k0, k1, k2, k3, t0, t1, t2, t3, vv;
;   float dd = 0.f;
;   const int qrow = tid >> 4, qc = tid & 15;
;   const int trow = tid >> 3, tc = tid & 7;
;   const int vrow = tid >> 2, vc = tid & 3;
;     ...
;   unsigned opk[8] = {0u, 0u, 0u, 0u, 0u, 0u, 0u, 0u};
;   size_t otok = 0;
;   SCAN_ISSUE(dir ? NC - 1 : 0);
	s_mul_i32 s11, s6, s7
	s_mov_b32 s12, s64
	s_mov_b32 s13, s65
	s_mul_i32 s0, s11, 0x10000
	s_add_u32 s12, s12, s0
	s_addc_u32 s13, s13, 0
	s_mul_i32 s0, s5, 0x100
	s_add_u32 s12, s12, s0
	s_addc_u32 s13, s13, 0
	s_add_u32 s14, s12, 0x2000000
	s_addc_u32 s15, s13, 0
	s_add_u32 s16, s88, 0x3d4c100
	s_addc_u32 s17, s89, 0
	s_mul_i32 s0, s11, 0x20000
	s_add_u32 s16, s16, s0
	s_addc_u32 s17, s17, 0
	s_mul_i32 s0, s5, 0x4000
	s_add_u32 s16, s16, s0
	s_addc_u32 s17, s17, 0
	s_add_u32 s18, s88, 0xdd4c500
	s_addc_u32 s19, s89, 0
	s_mul_i32 s0, s11, 0x50000
	s_add_u32 s18, s18, s0
	s_addc_u32 s19, s19, 0
	s_mul_i32 s0, s5, 0x100
	s_add_u32 s18, s18, s0
	s_addc_u32 s19, s19, 0
	s_mul_i32 s0, s3, 0x40
	s_add_u32 s18, s18, s0
	s_addc_u32 s19, s19, 0
	s_add_u32 s20, s88, 0x3b4c100
	s_addc_u32 s21, s89, 0
	s_mul_i32 s0, s11, 0x800
	s_add_u32 s20, s20, s0
	s_addc_u32 s21, s21, 0
	s_mul_i32 s0, s5, 0x200
	s_add_u32 s20, s20, s0
	s_addc_u32 s21, s21, 0
	s_add_u32 s22, s88, 0xdd4c100
	s_addc_u32 s23, s89, 0
	s_mul_i32 s0, s11, 0x50000
	s_add_u32 s22, s22, s0
	s_addc_u32 s23, s23, 0
	s_mul_i32 s0, s5, 0x100
	s_add_u32 s22, s22, s0
	s_addc_u32 s23, s23, 0
	s_mul_i32 s0, s3, 0x40
	s_add_u32 s22, s22, s0
	s_addc_u32 s23, s23, 0
	v_cmp_le_i32_e64 s[34:35], 0, v218
	v_cmp_le_i32_e64 s[36:37], 1, v218
	v_cmp_le_i32_e64 s[38:39], 2, v218
	v_cmp_le_i32_e64 s[40:41], 3, v218
	v_cmp_le_i32_e64 s[42:43], 8, v218
	v_cmp_le_i32_e64 s[44:45], 9, v218
	v_cmp_le_i32_e64 s[46:47], 10, v218
	v_cmp_le_i32_e64 s[48:49], 11, v218
	v_cmp_le_i32_e64 s[50:51], 16, v218
	v_cmp_le_i32_e64 s[52:53], 17, v218
	v_cmp_le_i32_e64 s[54:55], 18, v218
	v_cmp_le_i32_e64 s[56:57], 19, v218
	v_cmp_le_i32_e64 s[58:59], 24, v218
	v_cmp_le_i32_e64 s[60:61], 25, v218
	v_cmp_le_i32_e64 s[62:63], 26, v218
	v_cmp_le_i32_e64 s[64:65], 27, v218
	v_mov_b32_e32 v144, 0
	v_mov_b32_e32 v145, 0
	v_mov_b32_e32 v146, 0
	v_mov_b32_e32 v147, 0
	v_mov_b64_e32 v[112:113], v[144:145]
	v_mov_b64_e32 v[114:115], v[144:145]
	v_mov_b64_e32 v[116:117], v[144:145]
	v_mov_b64_e32 v[118:119], v[144:145]
	v_mov_b64_e32 v[120:121], v[144:145]
	v_mov_b64_e32 v[122:123], v[144:145]
	v_mov_b64_e32 v[124:125], v[144:145]
	v_mov_b64_e32 v[126:127], v[144:145]
	v_mov_b64_e32 v[128:129], v[144:145]
	v_mov_b64_e32 v[130:131], v[144:145]
	v_mov_b64_e32 v[132:133], v[144:145]
	v_mov_b64_e32 v[134:135], v[144:145]
	v_mov_b64_e32 v[136:137], v[144:145]
	v_mov_b64_e32 v[138:139], v[144:145]
	v_mov_b64_e32 v[140:141], v[144:145]
	v_mov_b64_e32 v[142:143], v[144:145]
	v_lshl_add_u32 v220, v53, 5, s31
	ds_write_b128 v220, v[144:147] offset:4608
	ds_write_b128 v220, v[144:147] offset:4624
	v_and_b32_e32 v221, 31, v53
	v_lshl_add_u32 v221, v221, 4, s31
	ds_write_b128 v221, v[144:147] offset:12800
	s_cmp_eq_u32 s26, 0
	s_cbranch_scc0 .Lsc0_nz
	s_cmp_eq_u32 s9, 1
	s_cbranch_scc0 .Lsc0_nz
	v_mul_u32_u24_e32 v219, 24, v109
	v_add_u32_e32 v219, v239, v219
	ds_write_b128 v219, v[144:147] offset:53248
	ds_write_b128 v219, v[144:147] offset:53264
.Lsc0_nz:
	s_mov_b32 s25, s9
	s_cmp_eq_u32 s9, 1
	s_cselect_b32 s25, 4, s25
	s_cmp_eq_u32 s26, 0
	s_cselect_b32 s25, s25, 4
	global_load_dwordx4 v[0:3], v209, s[12:13]
	global_load_dwordx4 v[4:7], v210, s[12:13]
	global_load_dwordx4 v[8:11], v209, s[14:15]
	global_load_dwordx4 v[12:15], v210, s[14:15]
	global_load_dwordx4 v[16:19], v213, s[16:17]
	global_load_dwordx4 v[20:23], v214, s[16:17]
	global_load_dwordx4 v[24:27], v215, s[18:19]
	global_load_dword v28, v216, s[20:21]
	s_sub_i32 s10, s7, 1
	s_cmp_gt_i32 s10, 0
	s_cselect_b32 s1, 1, 0
	s_sub_i32 s10, s10, s1
	s_mul_i32 s0, s1, 0x10000
	s_add_u32 s12, s12, s0
	s_addc_u32 s13, s13, 0
	s_mul_i32 s0, s1, 0x10000
	s_add_u32 s14, s14, s0
	s_addc_u32 s15, s15, 0
	s_mul_i32 s0, s1, 0x20000
	s_add_u32 s16, s16, s0
	s_addc_u32 s17, s17, 0
	s_mul_i32 s0, s1, 0x50000
	s_add_u32 s18, s18, s0
	s_addc_u32 s19, s19, 0
	s_mul_i32 s0, s1, 0x800
	s_add_u32 s20, s20, s0
	s_addc_u32 s21, s21, 0
	global_load_dwordx4 v[32:35], v209, s[12:13]
	global_load_dwordx4 v[36:39], v210, s[12:13]
	global_load_dwordx4 v[40:43], v209, s[14:15]
	global_load_dwordx4 v[44:47], v210, s[14:15]
	global_load_dwordx4 v[48:51], v213, s[16:17]
	global_load_dwordx4 v[52:55], v214, s[16:17]
	global_load_dwordx4 v[56:59], v215, s[18:19]
	global_load_dword v60, v216, s[20:21]
	s_cmp_lt_u32 s9, 2
	s_cbranch_scc0 .Lsc0_w1sfa
	s_waitcnt vmcnt(8)
	s_branch .Lsc0_w1efa
; DEV void scan_item_mfma(const Params& p, int g, int item, char* smem) {
;     ...
;     {
;       char* d = Qs + qrow * 272 + qc * 16;
;       *(uint4*)(d) = q0; *(uint4*)(d + 16 * 272) = q1; *(uint4*)(d + 32 * 272) = q2; *(uint4*)(d + 48 * 272) = q3;
;       d = Ks + qrow * 272 + qc * 16;
;       *(uint4*)(d) = k0; *(uint4*)(d + 16 * 272) = k1; *(uint4*)(d + 32 * 272) = k2; *(uint4*)(d + 48 * 272) = k3;
;       d = KTs + trow * 144 + tc * 16;
;       *(uint4*)(d) = t0; *(uint4*)(d + 32 * 144) = t1; *(uint4*)(d + 64 * 144) = t2; *(uint4*)(d + 96 * 144) = t3;
;       st8t(Vts + (vc * 8) * 144 + vrow * 2, vv);
;       if (tid < 128) decs[tid] = dd;
;       if (wave < 2 && ci > 0) {
;         u16* og = PHG + (otok + 32 * wave + 4 * hh) * 2560 + ocol + r;
; #pragma unroll
;         for (int i = 0; i < 8; ++i) {
;           og[(size_t)(((2 * i) & 3) + 8 * ((2 * i) >> 2)) * 2560] = (u16)(opk[i] & 0xffffu);
;           og[(size_t)(((2 * i + 1) & 3) + 8 * ((2 * i + 1) >> 2)) * 2560] = (u16)(opk[i] >> 16);
;         }
;       }
;       if (wave >= 2 && ci > 0) {
; #pragma unroll
;         for (int t = 0; t < 2; ++t) {
;           const int kt = 2 * (wave - 2) + t;
; #pragma unroll
;           for (int rg = 0; rg < 4; ++rg) {
;             const int kk0 = 32 * kt + 8 * rg + 4 * hh;
;             *(uint2*)(Sts + r * 272 + kk0 * 2) = make_uint2(pack2(accS[t][4 * rg + 0], accS[t][4 * rg + 1]),
;                                                             pack2(accS[t][4 * rg + 2], accS[t][4 * rg + 3]));
;           }
;         }
;       }
;     }
;     SCAN_BAR();
;     {
;       const int nn = (ci + 1 < NC) ? (dir ? NC - 2 - ci : ci + 1) : n;
;       SCAN_ISSUE(nn);
;     }
;     __builtin_amdgcn_sched_barrier(0);
;     {
;       const int jt = wave >> 1, st = wave & 1;
;       const bool active = dir ? (st >= jt) : (st <= jt);
;       f32x16 pa;
; #pragma unroll
;       for (int i = 0; i < 16; ++i) pa[i] = 0.f;
;       if (active) {
;         bf16x8 qa[8], kb[8];
; #pragma unroll
;         for (int ks = 0; ks < 8; ++ks) {
;           qa[ks] = *(const bf16x8*)(Qs + (32 * jt + r) * 272 + ks * 32 + hh * 16);
;           kb[ks] = *(const bf16x8*)(Ks + (32 * st + r) * 272 + ks * 32 + hh * 16);
;         }
;         __builtin_amdgcn_sched_barrier(0);
;         f32x16 p1;
; #pragma unroll
;         for (int i = 0; i < 16; ++i) p1[i] = 0.f;
; #pragma unroll
.Lsc0_w1sfa:
	s_waitcnt vmcnt(8)
.Lsc0_w1efa:
	ds_write_b128 v234, v[0:3] offset:0
	ds_write_b128 v234, v[4:7] offset:8704
	ds_write_b128 v234, v[8:11] offset:17408
	ds_write_b128 v234, v[12:15] offset:26112
	ds_write_b128 v235, v[16:19] offset:34816
	ds_write_b128 v235, v[20:23] offset:44032
	ds_write_b16 v236, v24 offset:0
	ds_write_b16_d16_hi v236, v24 offset:144
	ds_write_b16 v236, v25 offset:288
	ds_write_b16_d16_hi v236, v25 offset:432
	ds_write_b16 v236, v26 offset:576
	ds_write_b16_d16_hi v236, v26 offset:720
	ds_write_b16 v236, v27 offset:864
	ds_write_b16_d16_hi v236, v27 offset:1008
	ds_write_b32 v237, v28 offset:13312
	s_cmp_lt_u32 s9, 2
	s_cbranch_scc1 .Lsc0_p1ofa
	v_cvt_pk_bf16_f32 v166, v112, v113
	v_cvt_pk_bf16_f32 v167, v114, v115
	ds_write_b64 v238, v[166:167] offset:4608
	v_cvt_pk_bf16_f32 v168, v116, v117
	v_cvt_pk_bf16_f32 v169, v118, v119
	ds_write_b64 v238, v[168:169] offset:4624
	v_cvt_pk_bf16_f32 v170, v120, v121
	v_cvt_pk_bf16_f32 v171, v122, v123
	ds_write_b64 v238, v[170:171] offset:4640
	v_cvt_pk_bf16_f32 v172, v124, v125
	v_cvt_pk_bf16_f32 v173, v126, v127
	ds_write_b64 v238, v[172:173] offset:4656
	v_cvt_pk_bf16_f32 v174, v128, v129
	v_cvt_pk_bf16_f32 v175, v130, v131
	ds_write_b64 v238, v[174:175] offset:4672
	v_cvt_pk_bf16_f32 v176, v132, v133
	v_cvt_pk_bf16_f32 v177, v134, v135
	ds_write_b64 v238, v[176:177] offset:4688
	v_cvt_pk_bf16_f32 v178, v136, v137
	v_cvt_pk_bf16_f32 v179, v138, v139
	ds_write_b64 v238, v[178:179] offset:4704
	v_cvt_pk_bf16_f32 v180, v140, v141
	v_cvt_pk_bf16_f32 v181, v142, v143
	ds_write_b64 v238, v[180:181] offset:4720
.Lsc0_p1ofa:
	s_waitcnt lgkmcnt(0)
	s_barrier
	s_cmp_gt_i32 s10, 0
	s_cselect_b32 s1, 1, 0
	s_sub_i32 s10, s10, s1
	s_mul_i32 s0, s1, 0x10000
	s_add_u32 s12, s12, s0
	s_addc_u32 s13, s13, 0
	s_mul_i32 s0, s1, 0x10000
	s_add_u32 s14, s14, s0
	s_addc_u32 s15, s15, 0
	s_mul_i32 s0, s1, 0x20000
	s_add_u32 s16, s16, s0
	s_addc_u32 s17, s17, 0
	s_mul_i32 s0, s1, 0x50000
	s_add_u32 s18, s18, s0
	s_addc_u32 s19, s19, 0
	s_mul_i32 s0, s1, 0x800
	s_add_u32 s20, s20, s0
	s_addc_u32 s21, s21, 0
	global_load_dwordx4 v[0:3], v209, s[12:13]
	global_load_dwordx4 v[4:7], v210, s[12:13]
	global_load_dwordx4 v[8:11], v209, s[14:15]
	global_load_dwordx4 v[12:15], v210, s[14:15]
	global_load_dwordx4 v[16:19], v213, s[16:17]
	global_load_dwordx4 v[20:23], v214, s[16:17]
	global_load_dwordx4 v[24:27], v215, s[18:19]
	global_load_dword v28, v216, s[20:21]
	s_cmp_eq_u32 s25, 4
	s_cbranch_scc1 .Lsc0_p2efa
	ds_read_b128 v[166:169], v240
	ds_read_b128 v[170:173], v240 offset:32
	ds_read_b128 v[174:177], v240 offset:64
	ds_read_b128 v[178:181], v240 offset:96
	ds_read_b128 v[182:185], v242 offset:17408
	ds_read_b128 v[186:189], v242 offset:17440
	ds_read_b128 v[190:193], v242 offset:17472
	ds_read_b128 v[194:197], v242 offset:17504
	s_waitcnt lgkmcnt(0)
	v_mfma_f32_32x32x16_bf16 v[144:159], v[182:185], v[166:169], 0
	v_mfma_f32_32x32x16_bf16 v[144:159], v[186:189], v[170:173], v[144:159]
	v_mfma_f32_32x32x16_bf16 v[144:159], v[190:193], v[174:177], v[144:159]
	v_mfma_f32_32x32x16_bf16 v[144:159], v[194:197], v[178:181], v[144:159]
	ds_read_b128 v[166:169], v240 offset:128
	ds_read_b128 v[170:173], v240 offset:160
	ds_read_b128 v[174:177], v240 offset:192
	ds_read_b128 v[178:181], v240 offset:224
	ds_read_b128 v[182:185], v242 offset:17536
	ds_read_b128 v[186:189], v242 offset:17568
	ds_read_b128 v[190:193], v242 offset:17600
	ds_read_b128 v[194:197], v242 offset:17632
	s_waitcnt lgkmcnt(0)
	v_mfma_f32_32x32x16_bf16 v[144:159], v[182:185], v[166:169], v[144:159]
	v_mfma_f32_32x32x16_bf16 v[144:159], v[186:189], v[170:173], v[144:159]
	v_mfma_f32_32x32x16_bf16 v[144:159], v[190:193], v[174:177], v[144:159]
	v_mfma_f32_32x32x16_bf16 v[144:159], v[194:197], v[178:181], v[144:159]
	s_nop 7
	s_nop 7
	s_cmp_eq_u32 s25, 0
	s_cbranch_scc1 .Lsc0_p2mfa
	s_cmp_eq_u32 s25, 3
	s_cbranch_scc0 .Lsc0_p2nfa

; DEV void scan_item_mfma(const Params& p, int g, int item, char* smem) {
;     ...
; #pragma unroll
;       for (int i = 0; i < 16; ++i) {
;         const int j = 32 * jt + (i & 3) + 8 * (i >> 2) + 4 * hh;
;         const int s_ = 32 * st + r;
;         const bool keep = dir ? (s_ >= j) : (s_ <= j);
;         *(u16*)(Ps + j * 144 + s_ * 2) = keep ? f2bf(pa[i]) : (u16)0;
;       }
;     }
;     SCAN_BAR();
;     if (wave < 2) {
;       const int jt = wave;
;       bf16x8 pp[4], vb[4], qa[4], sb[4];
; #pragma unroll
;       for (int ks = 0; ks < 4; ++ks) {
;         pp[ks] = *(const bf16x8*)(Ps + (32 * jt + r) * 144 + ks * 32 + hh * 16);
;         vb[ks] = *(const bf16x8*)(Vts + r * 144 + ks * 32 + hh * 16);
;         qa[ks] = *(const bf16x8*)(Qs + (32 * jt + r) * 272 + ks * 32 + hh * 16);
;         sb[ks] = *(const bf16x8*)(Sts + r * 272 + ks * 32 + hh * 16);
;       }
;       __builtin_amdgcn_sched_barrier(0);
;       f32x16 o, o1;
; #pragma unroll
;       for (int i = 0; i < 16; ++i) { o[i] = 0.f; o1[i] = 0.f; }
; #pragma unroll
;       for (int ks = 0; ks < 4; ++ks) {
;         o = __builtin_amdgcn_mfma_f32_32x32x16_bf16(pp[ks], vb[ks], o, 0, 0, 0);
;         o1 = __builtin_amdgcn_mfma_f32_32x32x16_bf16(qa[ks], sb[ks], o1, 0, 0, 0);
;       }
;       __builtin_amdgcn_sched_barrier(0);
; #pragma unroll
;       for (int ks = 0; ks < 4; ++ks) {
;         qa[ks] = *(const bf16x8*)(Qs + (32 * jt + r) * 272 + (ks + 4) * 32 + hh * 16);
;         sb[ks] = *(const bf16x8*)(Sts + r * 272 + (ks + 4) * 32 + hh * 16);
;       }
;       __builtin_amdgcn_sched_barrier(0);
;       o = __builtin_amdgcn_mfma_f32_32x32x16_bf16(qa[0], sb[0], o, 0, 0, 0);
;       o1 = __builtin_amdgcn_mfma_f32_32x32x16_bf16(qa[1], sb[1], o1, 0, 0, 0);
;       o = __builtin_amdgcn_mfma_f32_32x32x16_bf16(qa[2], sb[2], o, 0, 0, 0);
;       o1 = __builtin_amdgcn_mfma_f32_32x32x16_bf16(qa[3], sb[3], o1, 0, 0, 0);
;       f32x16 o2;
; #pragma unroll
;       for (int i = 0; i < 16; ++i) o2[i] = 0.f;
; #pragma unroll
;       for (int i = 0; i < 8; ++i)
;         opk[i] = pack2(o[2 * i] + o1[2 * i] + o2[2 * i], o[2 * i + 1] + o1[2 * i + 1] + o2[2 * i + 1]);
;       otok = tok0;
;     } else {
;       const int kt0 = 2 * (wave - 2);
;       bf16x8 ka[2][4], vb[4];
; #pragma unroll
;       for (int ks = 0; ks < 4; ++ks) {
;         vb[ks] = *(const bf16x8*)(Vts + r * 144 + ks * 32 + hh * 16);
.Lsc0_p2nfa:
	v_cvt_pk_bf16_f32 v144, v144, v145
	v_cvt_pk_bf16_f32 v145, v146, v147
	ds_write_b64 v239, v[144:145] offset:53248
	v_cvt_pk_bf16_f32 v148, v148, v149
	v_cvt_pk_bf16_f32 v149, v150, v151
	ds_write_b64 v239, v[148:149] offset:53264
	v_cvt_pk_bf16_f32 v152, v152, v153
	v_cvt_pk_bf16_f32 v153, v154, v155
	ds_write_b64 v239, v[152:153] offset:53280
	v_cvt_pk_bf16_f32 v156, v156, v157
	v_cvt_pk_bf16_f32 v157, v158, v159
	ds_write_b64 v239, v[156:157] offset:53296
.Lsc0_p2efa:
	s_waitcnt lgkmcnt(0)
	s_barrier
	s_cmp_lt_u32 s9, 2
	s_cbranch_scc0 .Lsc0_p3sfa
	ds_read_b128 v[166:169], v243 offset:53248
	ds_read_b128 v[170:173], v243 offset:53280
	ds_read_b128 v[174:177], v243 offset:53312
	ds_read_b128 v[178:181], v243 offset:53344
	ds_read_b128 v[182:185], v244
	ds_read_b128 v[186:189], v244 offset:32
	ds_read_b128 v[190:193], v244 offset:64
	ds_read_b128 v[194:197], v244 offset:96
	ds_read_b128 v[198:201], v241
	ds_read_b128 v[222:225], v241 offset:32
	ds_read_b128 v[226:229], v241 offset:64
	ds_read_b128 v[230:233], v241 offset:96
	s_waitcnt lgkmcnt(4)
	v_mfma_f32_32x32x16_bf16 v[112:127], v[182:185], v[166:169], 0
	v_mfma_f32_32x32x16_bf16 v[112:127], v[186:189], v[170:173], v[112:127]
	v_mfma_f32_32x32x16_bf16 v[112:127], v[190:193], v[174:177], v[112:127]
	v_mfma_f32_32x32x16_bf16 v[112:127], v[194:197], v[178:181], v[112:127]
	ds_read_b128 v[166:169], v245 offset:4608
	ds_read_b128 v[170:173], v245 offset:4640
	ds_read_b128 v[174:177], v245 offset:4672
	ds_read_b128 v[178:181], v245 offset:4704
	s_waitcnt lgkmcnt(0)
	v_mfma_f32_32x32x16_bf16 v[112:127], v[166:169], v[198:201], v[112:127]
	v_mfma_f32_32x32x16_bf16 v[112:127], v[170:173], v[222:225], v[112:127]
	v_mfma_f32_32x32x16_bf16 v[112:127], v[174:177], v[226:229], v[112:127]
	v_mfma_f32_32x32x16_bf16 v[112:127], v[178:181], v[230:233], v[112:127]
	ds_read_b128 v[198:201], v241 offset:128
	ds_read_b128 v[222:225], v241 offset:160
	ds_read_b128 v[226:229], v241 offset:192
	ds_read_b128 v[230:233], v241 offset:224
	ds_read_b128 v[182:185], v245 offset:4736
	ds_read_b128 v[186:189], v245 offset:4768
	ds_read_b128 v[190:193], v245 offset:4800
	ds_read_b128 v[194:197], v245 offset:4832
	s_waitcnt lgkmcnt(0)
	v_mfma_f32_32x32x16_bf16 v[112:127], v[182:185], v[198:201], v[112:127]
	v_mfma_f32_32x32x16_bf16 v[112:127], v[186:189], v[222:225], v[112:127]
	v_mfma_f32_32x32x16_bf16 v[112:127], v[190:193], v[226:229], v[112:127]
	v_mfma_f32_32x32x16_bf16 v[112:127], v[194:197], v[230:233], v[112:127]
	s_nop 7
	s_nop 7
	v_cvt_pk_bf16_f32 v112, v112, v113
	v_cvt_pk_bf16_f32 v113, v114, v115
	global_store_dwordx2 v217, v[112:113], s[22:23] offset:0
	v_cvt_pk_bf16_f32 v116, v116, v117
	v_cvt_pk_bf16_f32 v117, v118, v119
	global_store_dwordx2 v217, v[116:117], s[22:23] offset:16
	v_cvt_pk_bf16_f32 v120, v120, v121
	v_cvt_pk_bf16_f32 v121, v122, v123
	global_store_dwordx2 v217, v[120:121], s[22:23] offset:32
	v_cvt_pk_bf16_f32 v124, v124, v125
	v_cvt_pk_bf16_f32 v125, v126, v127
	global_store_dwordx2 v217, v[124:125], s[22:23] offset:48
	s_branch .Lsc0_p3efa
.Lsc0_p3sfa:
	ds_read_b128 v[166:169], v244
	ds_read_b128 v[170:173], v244 offset:32
	ds_read_b128 v[174:177], v244 offset:64
	ds_read_b128 v[178:181], v244 offset:96
	ds_read_b128 v[182:185], v207 offset:34816
	ds_read_b128 v[186:189], v207 offset:34848
	ds_read_b128 v[190:193], v207 offset:34880
	ds_read_b128 v[194:197], v207 offset:34912
	ds_read_b128 v[198:201], v207 offset:39424
	ds_read_b128 v[222:225], v207 offset:39456
	ds_read_b128 v[226:229], v207 offset:39488
	ds_read_b128 v[230:233], v207 offset:39520
	s_waitcnt lgkmcnt(4)
	v_mfma_f32_32x32x16_bf16 v[112:127], v[182:185], v[166:169], v[112:127]
	v_mfma_f32_32x32x16_bf16 v[112:127], v[186:189], v[170:173], v[112:127]
	v_mfma_f32_32x32x16_bf16 v[112:127], v[190:193], v[174:177], v[112:127]
	v_mfma_f32_32x32x16_bf16 v[112:127], v[194:197], v[178:181], v[112:127]
	s_waitcnt lgkmcnt(0)
	v_mfma_f32_32x32x16_bf16 v[128:143], v[198:201], v[166:169], v[128:143]
	v_mfma_f32_32x32x16_bf16 v[128:143], v[222:225], v[170:173], v[128:143]
	v_mfma_f32_32x32x16_bf16 v[128:143], v[226:229], v[174:177], v[128:143]
	v_mfma_f32_32x32x16_bf16 v[128:143], v[230:233], v[178:181], v[128:143]
	ds_read_b128 v[166:169], v208 offset:13312
	ds_read_b128 v[170:173], v208 offset:13344
	ds_read_b128 v[174:177], v208 offset:13376
	ds_read_b128 v[178:181], v208 offset:13408
	ds_read_b128 v[182:185], v208 offset:13440
	ds_read_b128 v[186:189], v208 offset:13472
	ds_read_b128 v[190:193], v208 offset:13504
	ds_read_b128 v[194:197], v208 offset:13536
	s_nop 7
	s_nop 7
	s_waitcnt lgkmcnt(0)
	v_mul_f32_e32 v112, v112, v166
	v_mul_f32_e32 v113, v113, v167
	v_mul_f32_e32 v114, v114, v168
	v_mul_f32_e32 v115, v115, v169
	v_mul_f32_e32 v116, v116, v170
	v_mul_f32_e32 v117, v117, v171
	v_mul_f32_e32 v118, v118, v172
	v_mul_f32_e32 v119, v119, v173
	v_mul_f32_e32 v120, v120, v174
	v_mul_f32_e32 v121, v121, v175
	v_mul_f32_e32 v122, v122, v176
	v_mul_f32_e32 v123, v123, v177
	v_mul_f32_e32 v124, v124, v178
	v_mul_f32_e32 v125, v125, v179
	v_mul_f32_e32 v126, v126, v180
	v_mul_f32_e32 v127, v127, v181
	v_mul_f32_e32 v128, v128, v182
	v_mul_f32_e32 v129, v129, v183
	v_mul_f32_e32 v130, v130, v184
	v_mul_f32_e32 v131, v131, v185
	v_mul_f32_e32 v132, v132, v186
	v_mul_f32_e32 v133, v133, v187
	v_mul_f32_e32 v134, v134, v188
	v_mul_f32_e32 v135, v135, v189
	v_mul_f32_e32 v136, v136, v190
	v_mul_f32_e32 v137, v137, v191
	v_mul_f32_e32 v138, v138, v192
	v_mul_f32_e32 v139, v139, v193
	v_mul_f32_e32 v140, v140, v194
	v_mul_f32_e32 v141, v141, v195
	v_mul_f32_e32 v142, v142, v196
	v_mul_f32_e32 v143, v143, v197
.Lsc0_p3efa:
	s_mov_b32 s0, 0x50000
	s_add_u32 s22, s22, s0
	s_addc_u32 s23, s23, 0
	s_waitcnt lgkmcnt(0)
	s_barrier
	s_cmp_lt_u32 s9, 2
	s_cbranch_scc0 .Lsc0_w1sfb
	s_waitcnt vmcnt(12)
	s_branch .Lsc0_w1efb

; DEV void scan_item_mfma(const Params& p, int g, int item, char* smem) {
;     ...
;     {
;       char* d = Qs + qrow * 272 + qc * 16;
;       *(uint4*)(d) = q0; *(uint4*)(d + 16 * 272) = q1; *(uint4*)(d + 32 * 272) = q2; *(uint4*)(d + 48 * 272) = q3;
;       d = Ks + qrow * 272 + qc * 16;
;       *(uint4*)(d) = k0; *(uint4*)(d + 16 * 272) = k1; *(uint4*)(d + 32 * 272) = k2; *(uint4*)(d + 48 * 272) = k3;
;       d = KTs + trow * 144 + tc * 16;
;       *(uint4*)(d) = t0; *(uint4*)(d + 32 * 144) = t1; *(uint4*)(d + 64 * 144) = t2; *(uint4*)(d + 96 * 144) = t3;
;       st8t(Vts + (vc * 8) * 144 + vrow * 2, vv);
;       if (tid < 128) decs[tid] = dd;
;       if (wave < 2 && ci > 0) {
;         u16* og = PHG + (otok + 32 * wave + 4 * hh) * 2560 + ocol + r;
; #pragma unroll
;         for (int i = 0; i < 8; ++i) {
;           og[(size_t)(((2 * i) & 3) + 8 * ((2 * i) >> 2)) * 2560] = (u16)(opk[i] & 0xffffu);
;           og[(size_t)(((2 * i + 1) & 3) + 8 * ((2 * i + 1) >> 2)) * 2560] = (u16)(opk[i] >> 16);
;         }
;       }
;       if (wave >= 2 && ci > 0) {
; #pragma unroll
;         for (int t = 0; t < 2; ++t) {
;           const int kt = 2 * (wave - 2) + t;
; #pragma unroll
;           for (int rg = 0; rg < 4; ++rg) {
;             const int kk0 = 32 * kt + 8 * rg + 4 * hh;
;             *(uint2*)(Sts + r * 272 + kk0 * 2) = make_uint2(pack2(accS[t][4 * rg + 0], accS[t][4 * rg + 1]),
;                                                             pack2(accS[t][4 * rg + 2], accS[t][4 * rg + 3]));
;           }
;         }
;       }
;     }
;     SCAN_BAR();
;     {
;       const int nn = (ci + 1 < NC) ? (dir ? NC - 2 - ci : ci + 1) : n;
;       SCAN_ISSUE(nn);
;     }
;     __builtin_amdgcn_sched_barrier(0);
;     {
;       const int jt = wave >> 1, st = wave & 1;
;       const bool active = dir ? (st >= jt) : (st <= jt);
;       f32x16 pa;
; #pragma unroll
;       for (int i = 0; i < 16; ++i) pa[i] = 0.f;
;       if (active) {
;         bf16x8 qa[8], kb[8];
; #pragma unroll
;         for (int ks = 0; ks < 8; ++ks) {
;           qa[ks] = *(const bf16x8*)(Qs + (32 * jt + r) * 272 + ks * 32 + hh * 16);
;           kb[ks] = *(const bf16x8*)(Ks + (32 * st + r) * 272 + ks * 32 + hh * 16);
;         }
;         __builtin_amdgcn_sched_barrier(0);
;         f32x16 p1;
; #pragma unroll
;         for (int i = 0; i < 16; ++i) p1[i] = 0.f;
; #pragma unroll
.Lsc0_w1efb:
	ds_write_b128 v234, v[32:35] offset:0
	ds_write_b128 v234, v[36:39] offset:8704
	ds_write_b128 v234, v[40:43] offset:17408
	ds_write_b128 v234, v[44:47] offset:26112
	ds_write_b128 v235, v[48:51] offset:34816
	ds_write_b128 v235, v[52:55] offset:44032
	ds_write_b16 v236, v56 offset:0
	ds_write_b16_d16_hi v236, v56 offset:144
	ds_write_b16 v236, v57 offset:288
	ds_write_b16_d16_hi v236, v57 offset:432
	ds_write_b16 v236, v58 offset:576
	ds_write_b16_d16_hi v236, v58 offset:720
	ds_write_b16 v236, v59 offset:864
	ds_write_b16_d16_hi v236, v59 offset:1008
	ds_write_b32 v237, v60 offset:13312
	s_cmp_lt_u32 s9, 2
	s_cbranch_scc1 .Lsc0_p1ofb
	v_cvt_pk_bf16_f32 v166, v112, v113
	v_cvt_pk_bf16_f32 v167, v114, v115
	ds_write_b64 v238, v[166:167] offset:4608
	v_cvt_pk_bf16_f32 v168, v116, v117
	v_cvt_pk_bf16_f32 v169, v118, v119
	ds_write_b64 v238, v[168:169] offset:4624
	v_cvt_pk_bf16_f32 v170, v120, v121
	v_cvt_pk_bf16_f32 v171, v122, v123
	ds_write_b64 v238, v[170:171] offset:4640
	v_cvt_pk_bf16_f32 v172, v124, v125
	v_cvt_pk_bf16_f32 v173, v126, v127
	ds_write_b64 v238, v[172:173] offset:4656
	v_cvt_pk_bf16_f32 v174, v128, v129
	v_cvt_pk_bf16_f32 v175, v130, v131
	ds_write_b64 v238, v[174:175] offset:4672
	v_cvt_pk_bf16_f32 v176, v132, v133
	v_cvt_pk_bf16_f32 v177, v134, v135
	ds_write_b64 v238, v[176:177] offset:4688
	v_cvt_pk_bf16_f32 v178, v136, v137
	v_cvt_pk_bf16_f32 v179, v138, v139
	ds_write_b64 v238, v[178:179] offset:4704
	v_cvt_pk_bf16_f32 v180, v140, v141
	v_cvt_pk_bf16_f32 v181, v142, v143
	ds_write_b64 v238, v[180:181] offset:4720
.Lsc0_p1ofb:
	s_waitcnt lgkmcnt(0)
	s_barrier
	s_cmp_gt_i32 s10, 0
	s_cselect_b32 s1, 1, 0
	s_sub_i32 s10, s10, s1
	s_mul_i32 s0, s1, 0x10000
	s_add_u32 s12, s12, s0
	s_addc_u32 s13, s13, 0
	s_mul_i32 s0, s1, 0x10000
	s_add_u32 s14, s14, s0
	s_addc_u32 s15, s15, 0
	s_mul_i32 s0, s1, 0x20000
	s_add_u32 s16, s16, s0
	s_addc_u32 s17, s17, 0
	s_mul_i32 s0, s1, 0x50000
	s_add_u32 s18, s18, s0
	s_addc_u32 s19, s19, 0
	s_mul_i32 s0, s1, 0x800
	s_add_u32 s20, s20, s0
	s_addc_u32 s21, s21, 0
	global_load_dwordx4 v[32:35], v209, s[12:13]
	global_load_dwordx4 v[36:39], v210, s[12:13]
	global_load_dwordx4 v[40:43], v209, s[14:15]
	global_load_dwordx4 v[44:47], v210, s[14:15]
	global_load_dwordx4 v[48:51], v213, s[16:17]
	global_load_dwordx4 v[52:55], v214, s[16:17]
	global_load_dwordx4 v[56:59], v215, s[18:19]
	global_load_dword v60, v216, s[20:21]
	s_cmp_eq_u32 s25, 4
	s_cbranch_scc1 .Lsc0_p2efb
	ds_read_b128 v[166:169], v240
	ds_read_b128 v[170:173], v240 offset:32
	ds_read_b128 v[174:177], v240 offset:64
	ds_read_b128 v[178:181], v240 offset:96
	ds_read_b128 v[182:185], v242 offset:17408
	ds_read_b128 v[186:189], v242 offset:17440
	ds_read_b128 v[190:193], v242 offset:17472
	ds_read_b128 v[194:197], v242 offset:17504
	s_waitcnt lgkmcnt(0)
	v_mfma_f32_32x32x16_bf16 v[144:159], v[182:185], v[166:169], 0
	v_mfma_f32_32x32x16_bf16 v[144:159], v[186:189], v[170:173], v[144:159]
	v_mfma_f32_32x32x16_bf16 v[144:159], v[190:193], v[174:177], v[144:159]
	v_mfma_f32_32x32x16_bf16 v[144:159], v[194:197], v[178:181], v[144:159]
	ds_read_b128 v[166:169], v240 offset:128
	ds_read_b128 v[170:173], v240 offset:160
	ds_read_b128 v[174:177], v240 offset:192
	ds_read_b128 v[178:181], v240 offset:224
	ds_read_b128 v[182:185], v242 offset:17536
	ds_read_b128 v[186:189], v242 offset:17568
	ds_read_b128 v[190:193], v242 offset:17600
	ds_read_b128 v[194:197], v242 offset:17632
	s_waitcnt lgkmcnt(0)
	v_mfma_f32_32x32x16_bf16 v[144:159], v[182:185], v[166:169], v[144:159]
	v_mfma_f32_32x32x16_bf16 v[144:159], v[186:189], v[170:173], v[144:159]
	v_mfma_f32_32x32x16_bf16 v[144:159], v[190:193], v[174:177], v[144:159]
	v_mfma_f32_32x32x16_bf16 v[144:159], v[194:197], v[178:181], v[144:159]
	s_nop 7
	s_nop 7
	s_cmp_eq_u32 s25, 0
	s_cbranch_scc1 .Lsc0_p2mfb
	s_cmp_eq_u32 s25, 3
	s_cbranch_scc0 .Lsc0_p2nfb

; DEV void scan_item_mfma(const Params& p, int g, int item, char* smem) {
;     ...
;   for (int ci = 0; ci < NC; ++ci) {
;     const int n = dir ? NC - 1 - ci : ci;
;     const size_t tok0 = ((size_t)b * NC + n) * 64;
;     {
;       char* d = Qs + qrow * 272 + qc * 16;
;       *(uint4*)(d) = q0; *(uint4*)(d + 16 * 272) = q1; *(uint4*)(d + 32 * 272) = q2; *(uint4*)(d + 48 * 272) = q3;
;       d = Ks + qrow * 272 + qc * 16;
;       *(uint4*)(d) = k0; *(uint4*)(d + 16 * 272) = k1; *(uint4*)(d + 32 * 272) = k2; *(uint4*)(d + 48 * 272) = k3;
;       d = KTs + trow * 144 + tc * 16;
;       *(uint4*)(d) = t0; *(uint4*)(d + 32 * 144) = t1; *(uint4*)(d + 64 * 144) = t2; *(uint4*)(d + 96 * 144) = t3;
;       st8t(Vts + (vc * 8) * 144 + vrow * 2, vv);
.Lsc0_loop:
	s_cmp_lt_u32 s9, 2
	s_cbranch_scc0 .Lsc0_w1sa
	s_waitcnt vmcnt(16)
	s_branch .Lsc0_w1ea

; #define SCAN_BAR()                                        \
;   {                                                       \
;     asm volatile("s_waitcnt lgkmcnt(0)" ::: "memory");     \
;     __builtin_amdgcn_s_barrier();                         \
;     asm volatile("" ::: "memory");                         \
;   }
; DEV void scan_item_mfma(const Params& p, int g, int item, char* smem) {
;     ...
;   for (int ci = 0; ci < NC; ++ci) {
;     const int n = dir ? NC - 1 - ci : ci;
;     const size_t tok0 = ((size_t)b * NC + n) * 64;
;     {
;       char* d = Qs + qrow * 272 + qc * 16;
;       *(uint4*)(d) = q0; *(uint4*)(d + 16 * 272) = q1; *(uint4*)(d + 32 * 272) = q2; *(uint4*)(d + 48 * 272) = q3;
;     ...
;     SCAN_BAR();
;   }
.Lsc0_p3ea:
	s_mov_b32 s0, 0x50000
	s_add_u32 s22, s22, s0
	s_addc_u32 s23, s23, 0
	s_waitcnt lgkmcnt(0)
	s_barrier
	s_cmp_lt_u32 s9, 2
	s_cbranch_scc0 .Lsc0_w1sb
	s_waitcnt vmcnt(16)
	s_branch .Lsc0_w1eb

; #define SCAN_BAR()                                        \
;   {                                                       \
;     asm volatile("s_waitcnt lgkmcnt(0)" ::: "memory");     \
;     __builtin_amdgcn_s_barrier();                         \
;     asm volatile("" ::: "memory");                         \
;   }
; DEV void scan_item_mfma(const Params& p, int g, int item, char* smem) {
;     ...
;   for (int ci = 0; ci < NC; ++ci) {
;     const int n = dir ? NC - 1 - ci : ci;
;     const size_t tok0 = ((size_t)b * NC + n) * 64;
;     {
;       char* d = Qs + qrow * 272 + qc * 16;
;       *(uint4*)(d) = q0; *(uint4*)(d + 16 * 272) = q1; *(uint4*)(d + 32 * 272) = q2; *(uint4*)(d + 48 * 272) = q3;
;     ...
;     SCAN_BAR();
;   }
.Lsc0_p3eb:
	s_mov_b32 s0, 0x50000
	s_add_u32 s22, s22, s0
	s_addc_u32 s23, s23, 0
	s_waitcnt lgkmcnt(0)
	s_barrier
	s_sub_i32 s8, s8, 1
	s_cmp_lg_u32 s8, 0
	s_cbranch_scc1 .Lsc0_loop
	s_cmp_lt_u32 s9, 2
	s_cbranch_scc0 .Lsc0_w1sta
	s_waitcnt vmcnt(16)
	s_branch .Lsc0_w1eta

; #define SCAN_BAR()                                        \
;   {                                                       \
;     asm volatile("s_waitcnt lgkmcnt(0)" ::: "memory");     \
;     __builtin_amdgcn_s_barrier();                         \
;     asm volatile("" ::: "memory");                         \
;   }
; DEV void scan_item_mfma(const Params& p, int g, int item, char* smem) {
;     ...
;     SCAN_BAR();
;     {
;       const int nn = (ci + 1 < NC) ? (dir ? NC - 2 - ci : ci + 1) : n;
;       SCAN_ISSUE(nn);
;     }
;     __builtin_amdgcn_sched_barrier(0);
;     {
;       const int jt = wave >> 1, st = wave & 1;
;       const bool active = dir ? (st >= jt) : (st <= jt);
;       f32x16 pa;
; #pragma unroll
;       for (int i = 0; i < 16; ++i) pa[i] = 0.f;
;       if (active) {
;         bf16x8 qa[8], kb[8];
; #pragma unroll
;         for (int ks = 0; ks < 8; ++ks) {
;           qa[ks] = *(const bf16x8*)(Qs + (32 * jt + r) * 272 + ks * 32 + hh * 16);
;           kb[ks] = *(const bf16x8*)(Ks + (32 * st + r) * 272 + ks * 32 + hh * 16);
;         }
;         __builtin_amdgcn_sched_barrier(0);
;         f32x16 p1;
; #pragma unroll
;         for (int i = 0; i < 16; ++i) p1[i] = 0.f;
; #pragma unroll
;         for (int ks = 0; ks < 4; ++ks) {
;           pa = __builtin_amdgcn_mfma_f32_32x32x16_bf16(qa[2 * ks], kb[2 * ks], pa, 0, 0, 0);
;           p1 = __builtin_amdgcn_mfma_f32_32x32x16_bf16(qa[2 * ks + 1], kb[2 * ks + 1], p1, 0, 0, 0);
.Lsc0_p1ota:
	s_waitcnt lgkmcnt(0)
	s_barrier
	s_cmp_eq_u32 s25, 4
	s_cbranch_scc1 .Lsc0_p2eta
	ds_read_b128 v[166:169], v240
	ds_read_b128 v[170:173], v240 offset:32
	ds_read_b128 v[174:177], v240 offset:64
	ds_read_b128 v[178:181], v240 offset:96
	ds_read_b128 v[182:185], v242 offset:17408
	ds_read_b128 v[186:189], v242 offset:17440
	ds_read_b128 v[190:193], v242 offset:17472
	ds_read_b128 v[194:197], v242 offset:17504
	s_waitcnt lgkmcnt(0)
	v_mfma_f32_32x32x16_bf16 v[144:159], v[182:185], v[166:169], 0
	v_mfma_f32_32x32x16_bf16 v[144:159], v[186:189], v[170:173], v[144:159]
	v_mfma_f32_32x32x16_bf16 v[144:159], v[190:193], v[174:177], v[144:159]
	v_mfma_f32_32x32x16_bf16 v[144:159], v[194:197], v[178:181], v[144:159]
	ds_read_b128 v[166:169], v240 offset:128
	ds_read_b128 v[170:173], v240 offset:160
	ds_read_b128 v[174:177], v240 offset:192
	ds_read_b128 v[178:181], v240 offset:224
	ds_read_b128 v[182:185], v242 offset:17536
	ds_read_b128 v[186:189], v242 offset:17568
	ds_read_b128 v[190:193], v242 offset:17600
	ds_read_b128 v[194:197], v242 offset:17632
	s_waitcnt lgkmcnt(0)
	v_mfma_f32_32x32x16_bf16 v[144:159], v[182:185], v[166:169], v[144:159]
	v_mfma_f32_32x32x16_bf16 v[144:159], v[186:189], v[170:173], v[144:159]
	v_mfma_f32_32x32x16_bf16 v[144:159], v[190:193], v[174:177], v[144:159]
	v_mfma_f32_32x32x16_bf16 v[144:159], v[194:197], v[178:181], v[144:159]
	s_nop 7
	s_nop 7
	s_cmp_eq_u32 s25, 0
	s_cbranch_scc1 .Lsc0_p2mta
	s_cmp_eq_u32 s25, 3
	s_cbranch_scc0 .Lsc0_p2nta

; DEV void scan_item_mfma(const Params& p, int g, int item, char* smem) {
;     ...
;   unsigned opk[8] = {0u, 0u, 0u, 0u, 0u, 0u, 0u, 0u};
;   size_t otok = 0;
;   SCAN_ISSUE(dir ? NC - 1 : 0);
.Lscan_d1:
	s_mul_i32 s11, s6, s7
	s_add_i32 s11, s11, s7
	s_sub_i32 s11, s11, 1
	s_add_u32 s12, s64, 0x4000000
	s_addc_u32 s13, s65, 0
	s_mul_i32 s0, s11, 0x10000
	s_add_u32 s12, s12, s0
	s_addc_u32 s13, s13, 0
	s_mul_i32 s0, s5, 0x100
	s_add_u32 s12, s12, s0
	s_addc_u32 s13, s13, 0
	s_add_u32 s14, s12, 0x2000000
	s_addc_u32 s15, s13, 0
	s_add_u32 s16, s88, 0x3d5c100
	s_addc_u32 s17, s89, 0
	s_mul_i32 s0, s11, 0x20000
	s_add_u32 s16, s16, s0
	s_addc_u32 s17, s17, 0
	s_mul_i32 s0, s5, 0x4000
	s_add_u32 s16, s16, s0
	s_addc_u32 s17, s17, 0
	s_add_u32 s18, s88, 0xdd4c500
	s_addc_u32 s19, s89, 0
	s_mul_i32 s0, s11, 0x50000
	s_add_u32 s18, s18, s0
	s_addc_u32 s19, s19, 0
	s_mul_i32 s0, s5, 0x100
	s_add_u32 s18, s18, s0
	s_addc_u32 s19, s19, 0
	s_mul_i32 s0, s3, 0x40
	s_add_u32 s18, s18, s0
	s_addc_u32 s19, s19, 0
	s_add_u32 s20, s88, 0x3c4c100
	s_addc_u32 s21, s89, 0
	s_mul_i32 s0, s11, 0x800
	s_add_u32 s20, s20, s0
	s_addc_u32 s21, s21, 0
	s_mul_i32 s0, s5, 0x200
	s_add_u32 s20, s20, s0
	s_addc_u32 s21, s21, 0
	s_add_u32 s22, s88, 0xdd4c900
	s_addc_u32 s23, s89, 0
	s_mul_i32 s0, s11, 0x50000
	s_add_u32 s22, s22, s0
	s_addc_u32 s23, s23, 0
	s_mul_i32 s0, s5, 0x100
	s_add_u32 s22, s22, s0
	s_addc_u32 s23, s23, 0
	s_mul_i32 s0, s3, 0x40
	s_add_u32 s22, s22, s0
	s_addc_u32 s23, s23, 0
	v_cmp_ge_i32_e64 s[34:35], 0, v218
	v_cmp_ge_i32_e64 s[36:37], 1, v218
	v_cmp_ge_i32_e64 s[38:39], 2, v218
	v_cmp_ge_i32_e64 s[40:41], 3, v218
	v_cmp_ge_i32_e64 s[42:43], 8, v218
	v_cmp_ge_i32_e64 s[44:45], 9, v218
	v_cmp_ge_i32_e64 s[46:47], 10, v218
	v_cmp_ge_i32_e64 s[48:49], 11, v218
	v_cmp_ge_i32_e64 s[50:51], 16, v218
	v_cmp_ge_i32_e64 s[52:53], 17, v218
	v_cmp_ge_i32_e64 s[54:55], 18, v218
	v_cmp_ge_i32_e64 s[56:57], 19, v218
	v_cmp_ge_i32_e64 s[58:59], 24, v218
	v_cmp_ge_i32_e64 s[60:61], 25, v218
	v_cmp_ge_i32_e64 s[62:63], 26, v218
	v_cmp_ge_i32_e64 s[64:65], 27, v218
	v_mov_b32_e32 v144, 0
	v_mov_b32_e32 v145, 0
	v_mov_b32_e32 v146, 0
	v_mov_b32_e32 v147, 0
	v_mov_b64_e32 v[112:113], v[144:145]
	v_mov_b64_e32 v[114:115], v[144:145]
	v_mov_b64_e32 v[116:117], v[144:145]
	v_mov_b64_e32 v[118:119], v[144:145]
	v_mov_b64_e32 v[120:121], v[144:145]
	v_mov_b64_e32 v[122:123], v[144:145]
	v_mov_b64_e32 v[124:125], v[144:145]
	v_mov_b64_e32 v[126:127], v[144:145]
	v_mov_b64_e32 v[128:129], v[144:145]
	v_mov_b64_e32 v[130:131], v[144:145]
	v_mov_b64_e32 v[132:133], v[144:145]
	v_mov_b64_e32 v[134:135], v[144:145]
	v_mov_b64_e32 v[136:137], v[144:145]
	v_mov_b64_e32 v[138:139], v[144:145]
	v_mov_b64_e32 v[140:141], v[144:145]
	v_mov_b64_e32 v[142:143], v[144:145]
	v_lshl_add_u32 v220, v53, 5, s31
	ds_write_b128 v220, v[144:147] offset:4608
	ds_write_b128 v220, v[144:147] offset:4624
	v_and_b32_e32 v221, 31, v53
	v_lshl_add_u32 v221, v221, 4, s31
	ds_write_b128 v221, v[144:147] offset:12800
	s_cmp_eq_u32 s26, 0
	s_cbranch_scc0 .Lsc1_nz
	s_cmp_eq_u32 s9, 2
	s_cbranch_scc0 .Lsc1_nz
	v_mul_u32_u24_e32 v219, 24, v109
	v_add_u32_e32 v219, v239, v219
	ds_write_b128 v219, v[144:147] offset:53248
	ds_write_b128 v219, v[144:147] offset:53264
.Lsc1_nz:
	s_mov_b32 s25, s9
	s_cmp_eq_u32 s9, 2
	s_cselect_b32 s25, 4, s25
	s_cmp_eq_u32 s26, 0
	s_cselect_b32 s25, s25, 4
	global_load_dwordx4 v[0:3], v209, s[12:13]
	global_load_dwordx4 v[4:7], v210, s[12:13]
	global_load_dwordx4 v[8:11], v209, s[14:15]
	global_load_dwordx4 v[12:15], v210, s[14:15]
	global_load_dwordx4 v[16:19], v213, s[16:17]
	global_load_dwordx4 v[20:23], v214, s[16:17]
	global_load_dwordx4 v[24:27], v215, s[18:19]
	global_load_dword v28, v216, s[20:21]
	s_sub_i32 s10, s7, 1
	s_cmp_gt_i32 s10, 0
	s_cselect_b32 s1, 1, 0
	s_sub_i32 s10, s10, s1
	s_mul_i32 s0, s1, 0x10000
	s_sub_u32 s12, s12, s0
	s_subb_u32 s13, s13, 0
	s_mul_i32 s0, s1, 0x10000
	s_sub_u32 s14, s14, s0
	s_subb_u32 s15, s15, 0
	s_mul_i32 s0, s1, 0x20000
	s_sub_u32 s16, s16, s0
	s_subb_u32 s17, s17, 0
	s_mul_i32 s0, s1, 0x50000
	s_sub_u32 s18, s18, s0
	s_subb_u32 s19, s19, 0
	s_mul_i32 s0, s1, 0x800
	s_sub_u32 s20, s20, s0
	s_subb_u32 s21, s21, 0
	global_load_dwordx4 v[32:35], v209, s[12:13]
	global_load_dwordx4 v[36:39], v210, s[12:13]
	global_load_dwordx4 v[40:43], v209, s[14:15]
	global_load_dwordx4 v[44:47], v210, s[14:15]
	global_load_dwordx4 v[48:51], v213, s[16:17]
	global_load_dwordx4 v[52:55], v214, s[16:17]
	global_load_dwordx4 v[56:59], v215, s[18:19]
	global_load_dword v60, v216, s[20:21]
	s_cmp_lt_u32 s9, 2
	s_cbranch_scc0 .Lsc1_w1sfa
	s_waitcnt vmcnt(8)
	s_branch .Lsc1_w1efa

; #define SCAN_BAR()                                        \
;   {                                                       \
;     asm volatile("s_waitcnt lgkmcnt(0)" ::: "memory");     \
;     __builtin_amdgcn_s_barrier();                         \
;     asm volatile("" ::: "memory");                         \
;   }
; DEV void scan_item_mfma(const Params& p, int g, int item, char* smem) {
;     ...
;     SCAN_BAR();
;     {
;       const int nn = (ci + 1 < NC) ? (dir ? NC - 2 - ci : ci + 1) : n;
;       SCAN_ISSUE(nn);
;     }
;     __builtin_amdgcn_sched_barrier(0);
;     {
;       const int jt = wave >> 1, st = wave & 1;
;       const bool active = dir ? (st >= jt) : (st <= jt);
;       f32x16 pa;
; #pragma unroll
;       for (int i = 0; i < 16; ++i) pa[i] = 0.f;
;       if (active) {
;         bf16x8 qa[8], kb[8];
; #pragma unroll
;         for (int ks = 0; ks < 8; ++ks) {
;           qa[ks] = *(const bf16x8*)(Qs + (32 * jt + r) * 272 + ks * 32 + hh * 16);
;           kb[ks] = *(const bf16x8*)(Ks + (32 * st + r) * 272 + ks * 32 + hh * 16);
;         }
;         __builtin_amdgcn_sched_barrier(0);
;         f32x16 p1;
; #pragma unroll
;         for (int i = 0; i < 16; ++i) p1[i] = 0.f;
; #pragma unroll
;         for (int ks = 0; ks < 4; ++ks) {
;           pa = __builtin_amdgcn_mfma_f32_32x32x16_bf16(qa[2 * ks], kb[2 * ks], pa, 0, 0, 0);
;           p1 = __builtin_amdgcn_mfma_f32_32x32x16_bf16(qa[2 * ks + 1], kb[2 * ks + 1], p1, 0, 0, 0);
.Lsc1_p1ofa:
	s_waitcnt lgkmcnt(0)
	s_barrier
	s_cmp_gt_i32 s10, 0
	s_cselect_b32 s1, 1, 0
	s_sub_i32 s10, s10, s1
	s_mul_i32 s0, s1, 0x10000
	s_sub_u32 s12, s12, s0
	s_subb_u32 s13, s13, 0
	s_mul_i32 s0, s1, 0x10000
	s_sub_u32 s14, s14, s0
	s_subb_u32 s15, s15, 0
	s_mul_i32 s0, s1, 0x20000
	s_sub_u32 s16, s16, s0
	s_subb_u32 s17, s17, 0
	s_mul_i32 s0, s1, 0x50000
	s_sub_u32 s18, s18, s0
	s_subb_u32 s19, s19, 0
	s_mul_i32 s0, s1, 0x800
	s_sub_u32 s20, s20, s0
	s_subb_u32 s21, s21, 0
	global_load_dwordx4 v[0:3], v209, s[12:13]
	global_load_dwordx4 v[4:7], v210, s[12:13]
	global_load_dwordx4 v[8:11], v209, s[14:15]
	global_load_dwordx4 v[12:15], v210, s[14:15]
	global_load_dwordx4 v[16:19], v213, s[16:17]
	global_load_dwordx4 v[20:23], v214, s[16:17]
	global_load_dwordx4 v[24:27], v215, s[18:19]
	global_load_dword v28, v216, s[20:21]
	s_cmp_eq_u32 s25, 4
	s_cbranch_scc1 .Lsc1_p2efa
	ds_read_b128 v[166:169], v240
	ds_read_b128 v[170:173], v240 offset:32
	ds_read_b128 v[174:177], v240 offset:64
	ds_read_b128 v[178:181], v240 offset:96
	ds_read_b128 v[182:185], v242 offset:17408
	ds_read_b128 v[186:189], v242 offset:17440
	ds_read_b128 v[190:193], v242 offset:17472
	ds_read_b128 v[194:197], v242 offset:17504
	s_waitcnt lgkmcnt(0)
	v_mfma_f32_32x32x16_bf16 v[144:159], v[182:185], v[166:169], 0
	v_mfma_f32_32x32x16_bf16 v[144:159], v[186:189], v[170:173], v[144:159]
	v_mfma_f32_32x32x16_bf16 v[144:159], v[190:193], v[174:177], v[144:159]
	v_mfma_f32_32x32x16_bf16 v[144:159], v[194:197], v[178:181], v[144:159]
	ds_read_b128 v[166:169], v240 offset:128
	ds_read_b128 v[170:173], v240 offset:160
	ds_read_b128 v[174:177], v240 offset:192
	ds_read_b128 v[178:181], v240 offset:224
	ds_read_b128 v[182:185], v242 offset:17536
	ds_read_b128 v[186:189], v242 offset:17568
	ds_read_b128 v[190:193], v242 offset:17600
	ds_read_b128 v[194:197], v242 offset:17632
	s_waitcnt lgkmcnt(0)
	v_mfma_f32_32x32x16_bf16 v[144:159], v[182:185], v[166:169], v[144:159]
	v_mfma_f32_32x32x16_bf16 v[144:159], v[186:189], v[170:173], v[144:159]
	v_mfma_f32_32x32x16_bf16 v[144:159], v[190:193], v[174:177], v[144:159]
	v_mfma_f32_32x32x16_bf16 v[144:159], v[194:197], v[178:181], v[144:159]
	s_nop 7
	s_nop 7
	s_cmp_eq_u32 s25, 0
	s_cbranch_scc1 .Lsc1_p2mfa
	s_cmp_eq_u32 s25, 3
	s_cbranch_scc0 .Lsc1_p2nfa

; #define SCAN_BAR()                                        \
;   {                                                       \
;     asm volatile("s_waitcnt lgkmcnt(0)" ::: "memory");     \
;     __builtin_amdgcn_s_barrier();                         \
;     asm volatile("" ::: "memory");                         \
;   }
; DEV void scan_item_mfma(const Params& p, int g, int item, char* smem) {
;     ...
;   for (int ci = 0; ci < NC; ++ci) {
;     const int n = dir ? NC - 1 - ci : ci;
;     const size_t tok0 = ((size_t)b * NC + n) * 64;
;     {
;       char* d = Qs + qrow * 272 + qc * 16;
;       *(uint4*)(d) = q0; *(uint4*)(d + 16 * 272) = q1; *(uint4*)(d + 32 * 272) = q2; *(uint4*)(d + 48 * 272) = q3;
;     ...
;     SCAN_BAR();
;   }
.Lsc1_p3efa:
	s_mov_b32 s0, 0x50000
	s_sub_u32 s22, s22, s0
	s_subb_u32 s23, s23, 0
	s_waitcnt lgkmcnt(0)
	s_barrier
	s_cmp_lt_u32 s9, 2
	s_cbranch_scc0 .Lsc1_w1sfb
	s_waitcnt vmcnt(12)
	s_branch .Lsc1_w1efb

; #define SCAN_BAR()                                        \
;   {                                                       \
;     asm volatile("s_waitcnt lgkmcnt(0)" ::: "memory");     \
;     __builtin_amdgcn_s_barrier();                         \
;     asm volatile("" ::: "memory");                         \
;   }
; DEV void scan_item_mfma(const Params& p, int g, int item, char* smem) {
;     ...
;     SCAN_BAR();
;     {
;       const int nn = (ci + 1 < NC) ? (dir ? NC - 2 - ci : ci + 1) : n;
;       SCAN_ISSUE(nn);
;     }
;     __builtin_amdgcn_sched_barrier(0);
;     {
;       const int jt = wave >> 1, st = wave & 1;
;       const bool active = dir ? (st >= jt) : (st <= jt);
;       f32x16 pa;
; #pragma unroll
;       for (int i = 0; i < 16; ++i) pa[i] = 0.f;
;       if (active) {
;         bf16x8 qa[8], kb[8];
; #pragma unroll
;         for (int ks = 0; ks < 8; ++ks) {
;           qa[ks] = *(const bf16x8*)(Qs + (32 * jt + r) * 272 + ks * 32 + hh * 16);
;           kb[ks] = *(const bf16x8*)(Ks + (32 * st + r) * 272 + ks * 32 + hh * 16);
;         }
;         __builtin_amdgcn_sched_barrier(0);
;         f32x16 p1;
; #pragma unroll
;         for (int i = 0; i < 16; ++i) p1[i] = 0.f;
; #pragma unroll
;         for (int ks = 0; ks < 4; ++ks) {
;           pa = __builtin_amdgcn_mfma_f32_32x32x16_bf16(qa[2 * ks], kb[2 * ks], pa, 0, 0, 0);
;           p1 = __builtin_amdgcn_mfma_f32_32x32x16_bf16(qa[2 * ks + 1], kb[2 * ks + 1], p1, 0, 0, 0);
.Lsc1_p1ofb:
	s_waitcnt lgkmcnt(0)
	s_barrier
	s_cmp_gt_i32 s10, 0
	s_cselect_b32 s1, 1, 0
	s_sub_i32 s10, s10, s1
	s_mul_i32 s0, s1, 0x10000
	s_sub_u32 s12, s12, s0
	s_subb_u32 s13, s13, 0
	s_mul_i32 s0, s1, 0x10000
	s_sub_u32 s14, s14, s0
	s_subb_u32 s15, s15, 0
	s_mul_i32 s0, s1, 0x20000
	s_sub_u32 s16, s16, s0
	s_subb_u32 s17, s17, 0
	s_mul_i32 s0, s1, 0x50000
	s_sub_u32 s18, s18, s0
	s_subb_u32 s19, s19, 0
	s_mul_i32 s0, s1, 0x800
	s_sub_u32 s20, s20, s0
	s_subb_u32 s21, s21, 0
	global_load_dwordx4 v[32:35], v209, s[12:13]
	global_load_dwordx4 v[36:39], v210, s[12:13]
	global_load_dwordx4 v[40:43], v209, s[14:15]
	global_load_dwordx4 v[44:47], v210, s[14:15]
	global_load_dwordx4 v[48:51], v213, s[16:17]
	global_load_dwordx4 v[52:55], v214, s[16:17]
	global_load_dwordx4 v[56:59], v215, s[18:19]
	global_load_dword v60, v216, s[20:21]
	s_cmp_eq_u32 s25, 4
	s_cbranch_scc1 .Lsc1_p2efb
	ds_read_b128 v[166:169], v240
	ds_read_b128 v[170:173], v240 offset:32
	ds_read_b128 v[174:177], v240 offset:64
	ds_read_b128 v[178:181], v240 offset:96
	ds_read_b128 v[182:185], v242 offset:17408
	ds_read_b128 v[186:189], v242 offset:17440
	ds_read_b128 v[190:193], v242 offset:17472
	ds_read_b128 v[194:197], v242 offset:17504
	s_waitcnt lgkmcnt(0)
	v_mfma_f32_32x32x16_bf16 v[144:159], v[182:185], v[166:169], 0
	v_mfma_f32_32x32x16_bf16 v[144:159], v[186:189], v[170:173], v[144:159]
	v_mfma_f32_32x32x16_bf16 v[144:159], v[190:193], v[174:177], v[144:159]
	v_mfma_f32_32x32x16_bf16 v[144:159], v[194:197], v[178:181], v[144:159]
	ds_read_b128 v[166:169], v240 offset:128
	ds_read_b128 v[170:173], v240 offset:160
	ds_read_b128 v[174:177], v240 offset:192
	ds_read_b128 v[178:181], v240 offset:224
	ds_read_b128 v[182:185], v242 offset:17536
	ds_read_b128 v[186:189], v242 offset:17568
	ds_read_b128 v[190:193], v242 offset:17600
	ds_read_b128 v[194:197], v242 offset:17632
	s_waitcnt lgkmcnt(0)
	v_mfma_f32_32x32x16_bf16 v[144:159], v[182:185], v[166:169], v[144:159]
	v_mfma_f32_32x32x16_bf16 v[144:159], v[186:189], v[170:173], v[144:159]
	v_mfma_f32_32x32x16_bf16 v[144:159], v[190:193], v[174:177], v[144:159]
	v_mfma_f32_32x32x16_bf16 v[144:159], v[194:197], v[178:181], v[144:159]
	s_nop 7
	s_nop 7
	s_cmp_eq_u32 s25, 0
	s_cbranch_scc1 .Lsc1_p2mfb
	s_cmp_eq_u32 s25, 3
	s_cbranch_scc0 .Lsc1_p2nfb

; #define SCAN_BAR()                                        \
;   {                                                       \
;     asm volatile("s_waitcnt lgkmcnt(0)" ::: "memory");     \
;     __builtin_amdgcn_s_barrier();                         \
;     asm volatile("" ::: "memory");                         \
;   }
; DEV void scan_item_mfma(const Params& p, int g, int item, char* smem) {
;     ...
;   for (int ci = 0; ci < NC; ++ci) {
;     const int n = dir ? NC - 1 - ci : ci;
;     const size_t tok0 = ((size_t)b * NC + n) * 64;
;     {
;       char* d = Qs + qrow * 272 + qc * 16;
;       *(uint4*)(d) = q0; *(uint4*)(d + 16 * 272) = q1; *(uint4*)(d + 32 * 272) = q2; *(uint4*)(d + 48 * 272) = q3;
;     ...
;     SCAN_BAR();
;   }
.Lsc1_p3ea:
	s_mov_b32 s0, 0x50000
	s_sub_u32 s22, s22, s0
	s_subb_u32 s23, s23, 0
	s_waitcnt lgkmcnt(0)
	s_barrier
	s_cmp_lt_u32 s9, 2
	s_cbranch_scc0 .Lsc1_w1sb
	s_waitcnt vmcnt(16)
	s_branch .Lsc1_w1eb

; #define SCAN_BAR()                                        \
;   {                                                       \
;     asm volatile("s_waitcnt lgkmcnt(0)" ::: "memory");     \
;     __builtin_amdgcn_s_barrier();                         \
;     asm volatile("" ::: "memory");                         \
;   }
; DEV void scan_item_mfma(const Params& p, int g, int item, char* smem) {
;     ...
;   for (int ci = 0; ci < NC; ++ci) {
;     const int n = dir ? NC - 1 - ci : ci;
;     const size_t tok0 = ((size_t)b * NC + n) * 64;
;     {
;       char* d = Qs + qrow * 272 + qc * 16;
;       *(uint4*)(d) = q0; *(uint4*)(d + 16 * 272) = q1; *(uint4*)(d + 32 * 272) = q2; *(uint4*)(d + 48 * 272) = q3;
;     ...
;     SCAN_BAR();
;   }
.Lsc1_p3eb:
	s_mov_b32 s0, 0x50000
	s_sub_u32 s22, s22, s0
	s_subb_u32 s23, s23, 0
	s_waitcnt lgkmcnt(0)
	s_barrier
	s_sub_i32 s8, s8, 1
	s_cmp_lg_u32 s8, 0
	s_cbranch_scc1 .Lsc1_loop
	s_cmp_lt_u32 s9, 2
	s_cbranch_scc0 .Lsc1_w1sta
	s_waitcnt vmcnt(16)
	s_branch .Lsc1_w1eta
